# class-local deferred tiles (each deferred FFN-in tile is computed on the XCD class that consumes it) and no L2 write-back in their flag signals
# speedup vs baseline: 1.0087x; 1.0014x over previous
.Lko_late:
	s_cmp_lt_u32 s2, 0xa0
	s_cbranch_scc1 .Lko_none
	s_sub_i32 s4, s2, 0xa0
	s_lshr_b32 s4, s4, 3
	s_and_b32 s6, s2, 7
	s_cmp_eq_u32 s62, 3
	s_cbranch_scc1 .Lko_cl
	s_cmp_eq_u32 s62, 4
	s_cbranch_scc0 .Lko_none
	s_add_i32 s4, s4, 12
.Lko_cl:
	s_mov_b32 s7, 0
	s_cmp_eq_u32 s6, 1
	s_cselect_b32 s7, 3, s7
	s_cmp_eq_u32 s6, 0
	s_cselect_b32 s7, 5, s7
	s_add_i32 s4, s4, s7
	s_cmp_lt_u32 s4, 15
	s_cbranch_scc0 .Lko_none
	s_mul_i32 s7, s4, 0xcccd
	s_lshr_b32 s7, s7, 18
	s_add_i32 s64, s7, 19
	s_mul_i32 s7, s7, 5
	s_sub_i32 s4, s4, s7
	s_mul_i32 s6, s6, 5
	s_add_i32 s65, s6, s4
	s_branch .Lko_has

.Lko_nog:
	s_cmp_eq_u32 s100, 0
	s_cbranch_scc1 .Lko_nosig
	s_cmp_lt_u32 s62, 4
	s_cbranch_scc1 .Lko_nosig
	s_waitcnt vmcnt(0)
	s_barrier
	s_and_saveexec_b64 s[44:45], s[78:79]
	s_cbranch_execz .Lko_sigdone
	s_load_dwordx2 s[48:49], s[0:1], 0xe0
	s_cmp_eq_u32 s100, 2
	s_cbranch_scc1 .Lko_sig_nowb
	buffer_wbl2 sc1
.Lko_sig_nowb:
	s_lshl_b32 s4, s101, 6
	s_add_i32 s4, s4, s68
	s_lshl_b32 s4, s4, 2
	s_add_i32 s4, s4, s67
	s_sub_i32 s4, s4, 19
	s_lshl_b32 s4, s4, 2
	s_add_i32 s4, s4, 0x8000
	v_mov_b32_e32 v192, 0
	s_waitcnt vmcnt(0) lgkmcnt(0)
	s_add_u32 s48, s48, s4
	s_addc_u32 s49, s49, 0
	s_nop 4
	global_atomic_add v192, v252, s[48:49]
	s_waitcnt vmcnt(0)
